# S2: S1 + M3 sample-step loops (GDN, GLA) small q/k/v/gate loads issued together with one wait instead of load/wait chains
# baseline (speedup 1.0000x reference)
.LBB0_2020:
	s_ashr_i32 s43, s6, 3
	s_and_b32 s42, s6, 7
	s_add_i32 s6, s43, 0x2000
	s_ashr_i32 s7, s6, 31
	s_and_saveexec_b64 s[8:9], s[44:45]
	s_cbranch_execz .LBB0_2022
	s_mul_i32 s0, s6, 0x1800
	s_mul_hi_i32 s1, s6, 0x1800
	s_add_u32 s0, s31, s0
	v_lshl_add_u32 v90, s42, 7, v66
	s_addc_u32 s1, s34, s1
	v_ashrrev_i32_e32 v91, 31, v90
	v_lshl_add_u64 v[92:93], v[90:91], 1, s[0:1]
	global_load_ushort v86, v[92:93], off
	v_add_u32_e32 v92, 0x400, v90
	v_ashrrev_i32_e32 v93, 31, v92
	v_lshl_add_u64 v[92:93], v[92:93], 1, s[0:1]
	global_load_ushort v91, v[92:93], off
	v_add_u32_e32 v96, 0x800, v90
	v_ashrrev_i32_e32 v97, 31, v96
	v_lshl_add_u64 v[96:97], v[96:97], 1, s[0:1]
	global_load_ushort v96, v[96:97], off
	s_waitcnt vmcnt(0)
	v_lshlrev_b32_e32 v86, 16, v86
	v_lshlrev_b32_e32 v91, 16, v91
	ds_write2st64_b32 v87, v91, v86 offset1:2
	v_lshlrev_b32_e32 v96, 16, v96
	ds_write_b32 v87, v96 offset:1024

.LBB0_2031:
	s_and_b32 s43, s11, 3
	s_ashr_i32 s11, s11, 2
	s_add_i32 s6, s11, 0x2000
	s_ashr_i32 s7, s6, 31
	s_mul_i32 s1, s6, 0x9000
	s_mul_hi_i32 s0, s6, 0x9000
	s_add_u32 s8, s26, s1
	s_addc_u32 s9, s27, s0
	s_and_saveexec_b64 s[40:41], s[46:47]
	s_cbranch_execz .Lss_b_issued
	v_lshl_add_u32 v184, s43, 8, v175
	v_ashrrev_i32_e32 v185, 31, v184
	v_lshl_add_u64 v[184:185], v[184:185], 1, s[8:9]
	global_load_ushort v184, v[184:185], off
.Lss_b_issued:
	s_or_b64 exec, exec, s[40:41]
	s_and_saveexec_b64 s[40:41], s[44:45]
	s_cbranch_execz .LBB0_2033
	s_lshl_b64 s[0:1], s[6:7], 11
	s_add_u32 s0, s30, s0
	s_addc_u32 s1, s31, s1
	s_lshl_b32 s48, s43, 7
	v_add_u32_e32 v78, s48, v172
	v_ashrrev_i32_e32 v79, 31, v78
	v_lshl_add_u64 v[78:79], v[78:79], 1, s[8:9]
	global_load_ushort v78, v[78:79], off
	v_add_u32_e32 v80, s48, v174
	v_ashrrev_i32_e32 v81, 31, v80
	v_lshl_add_u64 v[80:81], v[80:81], 1, s[8:9]
	global_load_ushort v80, v[80:81], off
	v_add_u32_e32 v178, s48, v134
	v_ashrrev_i32_e32 v179, 31, v178
	v_lshl_add_u64 v[178:179], v[178:179], 2, s[0:1]
	global_load_dword v178, v[178:179], off
	s_waitcnt vmcnt(0)
	v_lshlrev_b32_e32 v78, 16, v78
	v_mul_f32_e32 v79, 0x3db504f3, v78
	v_lshlrev_b32_e32 v80, 16, v80
	ds_write2st64_b32 v173, v80, v79 offset1:2
	v_mul_f32_e32 v178, 0x3fb8aa3b, v178
	v_exp_f32_e32 v178, v178
	ds_write_b32 v173, v178 offset:1024
.LBB0_2033:
	s_or_b64 exec, exec, s[40:41]
	s_and_saveexec_b64 s[40:41], s[46:47]
	s_cbranch_execz .LBB0_2035
	s_waitcnt vmcnt(0)
	v_lshlrev_b32_e32 v184, 16, v184
	ds_write_b32 v173, v184 offset:1536
